# v74 plus D2 K/Q operand-load pipelining and D1 counted-wait load reorder
# speedup vs baseline: 1.0166x; 1.0028x over previous
; #define D1_LOAD(RH, RV, IT) do { const int it_ = (IT); const int s_ = it_ % 6, m0_ = (it_ / 6) * 16, ch_ = 512 * s_ + 8 * lane; \
;         _Pragma("unroll") for (int tt = 0; tt < 16; ++tt) RV[tt] = *(gcu)(PROJ + (size_t)(m0_ + tt) * NPROJ + ch_); } while (0)
; DI void d1_phase(const Params& P, int l, int gw, int NGW, int lane) {
;     ...
; #pragma unroll 1
;     for (int it = gw; it < NIT; it += 2 * NGW) {
;         if (it + NGW < NIT) D1_LOAD(hB, vB, it + NGW);
;         D1_COMPUTE(hA, vA, it);
;         if (it + NGW < NIT) {
.LBB0_496:
	s_add_i32 s19, s23, s14
	s_cmp_lt_i32 s19, s70
	s_cselect_b64 s[40:41], -1, 0
	s_cmp_ge_i32 s19, s70
	s_mul_hi_i32 s15, s19, 0x2aaaaaab
	s_cbranch_scc1 .LBB0_498
	s_lshr_b32 s0, s15, 31
	s_add_i32 s0, s15, s0
	s_mul_i32 s1, s0, 6
	s_sub_i32 s1, s19, s1
	s_lshl_b32 s8, s0, 4
	v_lshl_or_b32 v64, s1, 9, v191
	v_readlane_b32 s0, v255, 6
	v_ashrrev_i32_e32 v65, 31, v64
	v_readlane_b32 s1, v255, 7
	s_nop 1
	v_lshl_add_u64 v[122:123], v[64:65], 1, s[0:1]
	v_mad_i64_i32 v[64:65], s[0:1], s8, v237, v[122:123]
	s_or_b32 s0, s8, 1
	s_nop 0
	v_mad_i64_i32 v[68:69], s[0:1], s0, v237, v[122:123]
	s_or_b32 s0, s8, 2
	s_nop 0
	v_mad_i64_i32 v[72:73], s[0:1], s0, v237, v[122:123]
	s_or_b32 s0, s8, 3
	s_nop 0
	v_mad_i64_i32 v[76:77], s[0:1], s0, v237, v[122:123]
	s_or_b32 s0, s8, 4
	s_nop 0
	v_mad_i64_i32 v[80:81], s[0:1], s0, v237, v[122:123]
	s_or_b32 s0, s8, 5
	s_nop 0
	v_mad_i64_i32 v[84:85], s[0:1], s0, v237, v[122:123]
	s_or_b32 s0, s8, 6
	s_nop 0
	v_mad_i64_i32 v[88:89], s[0:1], s0, v237, v[122:123]
	s_or_b32 s0, s8, 7
	s_nop 0
	v_mad_i64_i32 v[92:93], s[0:1], s0, v237, v[122:123]
	s_or_b32 s0, s8, 8
	s_nop 0
	v_mad_i64_i32 v[98:99], s[0:1], s0, v237, v[122:123]
	s_or_b32 s0, s8, 9
	s_nop 0
	v_mad_i64_i32 v[102:103], s[0:1], s0, v237, v[122:123]
	s_or_b32 s0, s8, 10
	s_nop 0
	v_mad_i64_i32 v[106:107], s[0:1], s0, v237, v[122:123]
	s_or_b32 s0, s8, 11
	s_nop 0
	v_mad_i64_i32 v[110:111], s[0:1], s0, v237, v[122:123]
	s_or_b32 s0, s8, 12
	s_nop 0
	v_mad_i64_i32 v[114:115], s[0:1], s0, v237, v[122:123]
	s_or_b32 s0, s8, 13
	s_nop 0
	v_mad_i64_i32 v[118:119], s[0:1], s0, v237, v[122:123]
	s_or_b32 s0, s8, 14
	s_nop 0
	v_mad_i64_i32 v[124:125], s[0:1], s0, v237, v[122:123]
	s_or_b32 s0, s8, 15
	s_nop 0
	v_mad_i64_i32 v[126:127], s[0:1], s0, v237, v[122:123]
	s_movk_i32 s1, 0x3000

; #define D1_LOAD(RH, RV, IT) do { const int it_ = (IT); const int s_ = it_ % 6, m0_ = (it_ / 6) * 16, ch_ = 512 * s_ + 8 * lane; \
;         _Pragma("unroll") for (int tt = 0; tt < 16; ++tt) RV[tt] = *(gcu)(PROJ + (size_t)(m0_ + tt) * NPROJ + ch_); } while (0)
; DI void d1_phase(const Params& P, int l, int gw, int NGW, int lane) {
;     ...
;     u32x4 vA[16], vB[16]; int hA = 0, hB = 0; (void)hA; (void)hB;
;     if (gw < NIT) D1_LOAD(hA, vA, gw);
; #pragma unroll 1
;     for (int it = gw; it < NIT; it += 2 * NGW) {
;         if (it + NGW < NIT) D1_LOAD(hB, vB, it + NGW);
;         D1_COMPUTE(hA, vA, it);
;         if (it + NGW < NIT) {
;             if (it + 2 * NGW < NIT) D1_LOAD(hA, vA, it + 2 * NGW);
;             D1_COMPUTE(hB, vB, it + NGW);
;         }
.LBB0_537:
	v_pk_mul_f32 v[130:131], v[130:131], v[168:169] op_sel_hi:[1,0]
	v_pk_mul_f32 v[136:137], v[146:147], v[168:169] op_sel_hi:[1,0]
	v_pk_mul_f32 v[132:133], v[132:133], v[168:169] op_sel_hi:[1,0]
	v_cvt_pk_bf16_f32 v138, v130, v131
	v_pk_mul_f32 v[130:131], v[134:135], v[168:169] op_sel_hi:[1,0]
	s_movk_i32 s0, 0x800
	v_cvt_pk_bf16_f32 v136, v136, v137
	v_cvt_pk_bf16_f32 v137, v132, v133
	v_cvt_pk_bf16_f32 v139, v130, v131
	s_andn2_b64 vcc, exec, s[40:41]
	s_add_i32 s14, s14, s0
	global_store_dwordx4 v[162:163], v[136:139], off offset:3840
	s_cbranch_vccnz .LBB0_495
	s_movk_i32 s9, 0x3000
	s_cmp_ge_i32 s14, s70
	s_cbranch_scc1 .LBB0_540
	s_mul_hi_i32 s0, s14, 0x2aaaaaab
	s_lshr_b32 s1, s0, 31
	s_add_i32 s0, s0, s1
	s_lshl_b32 s8, s0, 4
	s_mulk_i32 s0, 0xf400
	s_add_i32 s0, s0, s12
	v_add_u32_e32 v0, s0, v218
	v_readlane_b32 s0, v255, 6
	v_ashrrev_i32_e32 v1, 31, v0
	v_readlane_b32 s1, v255, 7
	s_nop 1
	v_lshl_add_u64 v[56:57], v[0:1], 1, s[0:1]
	v_mad_i64_i32 v[0:1], s[0:1], s8, v237, v[56:57]
	s_or_b32 s0, s8, 1
	s_nop 0
	v_mad_i64_i32 v[4:5], s[0:1], s0, v237, v[56:57]
	s_or_b32 s0, s8, 2
	s_nop 0
	v_mad_i64_i32 v[8:9], s[0:1], s0, v237, v[56:57]
	s_or_b32 s0, s8, 3
	s_nop 0
	v_mad_i64_i32 v[12:13], s[0:1], s0, v237, v[56:57]
	s_or_b32 s0, s8, 4
	s_nop 0
	v_mad_i64_i32 v[16:17], s[0:1], s0, v237, v[56:57]
	s_or_b32 s0, s8, 5
	s_nop 0
	v_mad_i64_i32 v[20:21], s[0:1], s0, v237, v[56:57]
	s_or_b32 s0, s8, 6
	s_nop 0
	v_mad_i64_i32 v[24:25], s[0:1], s0, v237, v[56:57]
	s_or_b32 s0, s8, 7
	s_nop 0
	v_mad_i64_i32 v[28:29], s[0:1], s0, v237, v[56:57]
	s_or_b32 s0, s8, 8
	s_nop 0
	v_mad_i64_i32 v[32:33], s[0:1], s0, v237, v[56:57]
	s_or_b32 s0, s8, 9
	s_nop 0
	v_mad_i64_i32 v[36:37], s[0:1], s0, v237, v[56:57]
	s_or_b32 s0, s8, 10
	s_nop 0
	v_mad_i64_i32 v[40:41], s[0:1], s0, v237, v[56:57]
	s_or_b32 s0, s8, 11
	s_nop 0
	v_mad_i64_i32 v[44:45], s[0:1], s0, v237, v[56:57]
	s_or_b32 s0, s8, 12
	s_nop 0
	v_mad_i64_i32 v[48:49], s[0:1], s0, v237, v[56:57]
	s_or_b32 s0, s8, 13
	s_nop 0
	v_mad_i64_i32 v[52:53], s[0:1], s0, v237, v[56:57]
	s_or_b32 s0, s8, 14
	s_nop 0
	v_mad_i64_i32 v[58:59], s[0:1], s0, v237, v[56:57]
	s_or_b32 s0, s8, 15
	s_nop 0
	v_mad_i64_i32 v[60:61], s[0:1], s0, v237, v[56:57]
.LBB0_540:
	s_lshr_b32 s11, s15, 31
	s_add_i32 s0, s15, s11
	s_mul_i32 s1, s0, 6
	s_sub_i32 s20, s19, s1
	v_lshl_or_b32 v178, s20, 9, v191
	v_ashrrev_i32_e32 v179, 31, v178
	v_lshl_add_u64 v[142:143], v[178:179], 2, s[4:5]
	v_add_co_u32_e32 v136, vcc, s9, v142
	s_movk_i32 s1, 0x6000
	s_nop 0
	v_addc_co_u32_e32 v137, vcc, 0, v143, vcc
	s_mov_b64 s[8:9], 0x6000
	v_add_co_u32_e32 v140, vcc, s1, v142
	s_mov_b64 s[36:37], 0x3000
	v_lshl_add_u64 v[138:139], v[142:143], 0, s[8:9]
	v_addc_co_u32_e32 v141, vcc, 0, v143, vcc
	s_mov_b64 s[8:9], 0x9000
	s_mov_b32 s1, 0x9000
	global_load_dwordx4 v[130:133], v[142:143], off offset:16
	global_load_dwordx4 v[146:149], v[142:143], off
	v_lshl_add_u64 v[134:135], v[142:143], 0, s[36:37]
	v_lshl_add_u64 v[144:145], v[142:143], 0, s[8:9]
	v_add_co_u32_e32 v142, vcc, s1, v142
	global_load_dwordx4 v[150:153], v[136:137], off
	s_nop 0
	global_load_dwordx4 v[134:137], v[134:135], off offset:16
	v_addc_co_u32_e32 v143, vcc, 0, v143, vcc
	global_load_dwordx4 v[154:157], v[140:141], off
	s_nop 0
	global_load_dwordx4 v[138:141], v[138:139], off offset:16
	s_nop 0
	global_load_dwordx4 v[158:161], v[142:143], off
	s_nop 0
	global_load_dwordx4 v[142:145], v[144:145], off offset:16
	s_lshl_b32 s19, s0, 4
	s_bfe_i32 s0, s0, 0x1001b
	s_lshr_b32 s0, s0, 19
	s_add_i32 s0, s19, s0
	s_and_b32 s0, s0, 0xffffe000
	s_sub_i32 s10, s19, s0
	v_readlane_b32 s0, v255, 6
	s_cmp_gt_i32 s10, 0
	v_readlane_b32 s1, v255, 7
	s_cselect_b64 s[8:9], -1, 0
	s_cmp_lt_i32 s10, 1
	v_lshl_add_u64 v[174:175], v[178:179], 1, s[0:1]
	s_cbranch_scc1 .LBB0_542
	s_add_i32 s0, s19, -3
	v_mad_i64_i32 v[162:163], s[0:1], s0, v237, v[174:175]
	global_load_dwordx4 v[162:165], v[162:163], off
	s_branch .LBB0_543

; #define D1_LOAD(RH, RV, IT) do { const int it_ = (IT); const int s_ = it_ % 6, m0_ = (it_ / 6) * 16, ch_ = 512 * s_ + 8 * lane; \
;         _Pragma("unroll") for (int tt = 0; tt < 16; ++tt) RV[tt] = *(gcu)(PROJ + (size_t)(m0_ + tt) * NPROJ + ch_); } while (0)
; DI void d1_phase(const Params& P, int l, int gw, int NGW, int lane) {
;     ...
; #pragma unroll 1
;     for (int it = gw; it < NIT; it += 2 * NGW) {
;         if (it + NGW < NIT) D1_LOAD(hB, vB, it + NGW);
;         D1_COMPUTE(hA, vA, it);
;         if (it + NGW < NIT) {
;             if (it + 2 * NGW < NIT) D1_LOAD(hA, vA, it + 2 * NGW);
;             D1_COMPUTE(hB, vB, it + NGW);
;         }
.LBB0_547:
	s_cmp_ge_i32 s14, s70
	s_cbranch_scc1 .Ld1b_nonext
	global_load_dwordx4 v[0:3], v[0:1], off
	global_load_dwordx4 v[4:7], v[4:5], off
	global_load_dwordx4 v[8:11], v[8:9], off
	global_load_dwordx4 v[12:15], v[12:13], off
	global_load_dwordx4 v[16:19], v[16:17], off
	global_load_dwordx4 v[20:23], v[20:21], off
	global_load_dwordx4 v[24:27], v[24:25], off
	global_load_dwordx4 v[28:31], v[28:29], off
	global_load_dwordx4 v[32:35], v[32:33], off
	global_load_dwordx4 v[36:39], v[36:37], off
	global_load_dwordx4 v[40:43], v[40:41], off
	global_load_dwordx4 v[44:47], v[44:45], off
	global_load_dwordx4 v[48:51], v[48:49], off
	global_load_dwordx4 v[52:55], v[52:53], off
	global_load_dwordx4 v[56:59], v[58:59], off
	global_load_dwordx4 v[60:63], v[60:61], off
	s_waitcnt vmcnt(16)
	s_branch .Ld1b_go
